# scan (step 11): static s_setprio 2 for the four compute waves over the chunk loop so the serial MFMA chain wins issue arbitration against the loader waves
# speedup vs baseline: 1.0065x; 1.0060x over previous
; #define GAS __attribute__((address_space(1)))
; #define LDS_BARRIER() do { asm volatile("s_waitcnt lgkmcnt(0)" ::: "memory"); __builtin_amdgcn_s_barrier(); asm volatile("" ::: "memory"); } while (0)
; #define LAUNDER_V(x) asm volatile("" : "+v"(x))
; #define LD_T(F, base_) do { _Pragma("unroll") for (int ti = 0; ti < 4; ++ti) _Pragma("unroll") for (int k2 = 0; k2 < 2; ++k2) { const h16* tp = (base_) + (16 * ti + fr) * 72 + 32 * k2 + 4 * g; \
;                     F[2 * ti + k2] = cat8(*(const h16x4*)tp, *(const h16x4*)(tp + 16)); } } while (0)
; __device__ __forceinline__ void phase_scan(h16* Pdn, const h16* Tg, const h16* qkg, const float* gcg, const float* betag, const float* s2g, unsigned char* ldsb) {
;     ...
;         const int item = bid;
;         const int bh = (item & 7) * 8 + (item >> 4), s = (item >> 3) & 1, b = bh >> 3, h = bh & 7;
;         f32x4 S[8];
; #pragma unroll
;         for (int tk = 0; tk < 8; ++tk) S[tk] = (f32x4){0.f, 0.f, 0.f, 0.f};
;     ...
;         int tc = tid; LAUNDER_V(tc);
;         const int lane = tc & 63, fr = lane & 15, g = lane >> 4; (void)lane;
;         LDS_BARRIER();
; #pragma unroll 1
;         for (int n = 0; n < 64; ++n) {
;             const unsigned tok0 = (unsigned)b * SEQ + 64 * n;
;             const h16* B = (const h16*)ldsb + (n & 1) * BUFH;
;             const h16* qn = B + OQ; const h16* kn = B + OK_; const h16* Tm = B + OT; const h16* qkm = B + OQK; const h16* vbs = B + OV;
;             const float* gcs = (const float*)(B + OSC); const float* bts = gcs + 64; const float* s2s = gcs + 128;
;             {
;                 GAS h16* ob = (GAS h16*)(Pdn + (tok0 * 4096 + 2048 + h * 128 + 64 * s));
;                 const float e_last = gcs[63];
;                 h16x8 Sf[4];
; #pragma unroll
;                 for (int kk = 0; kk < 4; ++kk)
; #pragma unroll
;                     for (int rg = 0; rg < 4; ++rg) { Sf[kk][rg] = (h16)S[2 * kk][rg]; Sf[kk][4 + rg] = (h16)S[2 * kk + 1][rg]; }
;     ...
;                 h16x8 F0[8], F1[8];
;                 f32x4 gc0, bt0, gc1 = {0.f, 0.f, 0.f, 0.f}, bt1 = {0.f, 0.f, 0.f, 0.f}; h16x4 vb0, vb1 = {0, 0, 0, 0};
;                 LD_A(F0, 0); LD_S(gc0, bt0, vb0, 0);
;                 f32x4 R[4], O[4];
; #pragma unroll
;                 for (int ti = 0; ti < 4; ++ti) {
;                     if (ti < 3) { LD_A(F1, ti + 1); LD_S(gc1, bt1, vb1, ti + 1); } else LD_T(F1, Tm);
.LBB0_243:
	s_and_b64 vcc, exec, s[0:1]
	s_cbranch_vccz .LBB0_283
	v_mov_b32_e32 v170, v192
	s_mov_b32 s0, s52
	s_cmpk_gt_i32 s0, 0x7f
	v_readfirstlane_b32 s1, v170
	s_cbranch_scc1 .LBB0_283
	s_ashr_i32 s6, s1, 6
	s_lshl_b32 s1, s0, 3
	s_and_b32 s4, s1, 56
	s_ashr_i32 s1, s0, 4
	s_add_i32 s4, s4, s1
	s_ashr_i32 s5, s4, 3
	s_bfe_u32 s3, s0, 0x10003
	s_and_b32 s8, s1, 7
	s_cmp_lt_i32 s6, 4
	s_mov_b64 s[0:1], -1
	s_cbranch_scc0 .LBB0_249
	v_mov_b32_e32 v0, v170
	s_lshl_b32 s6, s6, 4
	v_lshrrev_b32_e32 v3, 2, v0
	v_and_b32_e32 v1, 15, v0
	v_and_b32_e32 v171, 12, v3
	v_bfe_u32 v3, v0, 2, 4
	v_lshlrev_b32_e32 v0, 2, v0
	s_lshl_b32 s0, s5, 24
	s_lshl_b32 s1, s8, 7
	v_and_b32_e32 v4, 12, v0
	v_or_b32_e32 v0, s6, v1
	s_waitcnt lgkmcnt(0)
	s_barrier
	s_lshl_b32 s9, s3, 6
	v_lshl_add_u32 v138, v171, 12, v0
	s_or_b32 s0, s0, s1
	v_readlane_b32 s36, v254, 43
	v_mul_u32_u24_e32 v2, 0x88, v1
	v_add_u32_e32 v140, 0x1000, v138
	v_add_u32_e32 v142, 0x2000, v138
	v_add_u32_e32 v144, 0x3000, v138
	v_add_u32_e32 v146, 0x10000, v138
	v_add_u32_e32 v148, 0x11000, v138
	v_add_u32_e32 v150, 0x12000, v138
	v_add_u32_e32 v152, 0x13000, v138
	v_add_u32_e32 v154, 0x20000, v138
	v_add_u32_e32 v156, 0x21000, v138
	v_add_u32_e32 v158, 0x22000, v138
	v_add_u32_e32 v160, 0x23000, v138
	v_add_u32_e32 v162, 0x30000, v138
	v_add_u32_e32 v164, 0x31000, v138
	v_add_u32_e32 v166, 0x32000, v138
	v_add_u32_e32 v168, 0x33000, v138
	v_lshlrev_b32_e32 v175, 1, v171
	s_or_b32 s0, s0, s9
	v_readlane_b32 s45, v254, 52
	v_mov_b32_e32 v0, 0
	v_lshlrev_b32_e32 v172, 7, v3
	v_mul_u32_u24_e32 v173, 0x90, v1
	v_mul_u32_u24_e32 v174, 0x110, v3
	v_ashrrev_i32_e32 v139, 31, v138
	v_ashrrev_i32_e32 v141, 31, v140
	v_ashrrev_i32_e32 v143, 31, v142
	v_ashrrev_i32_e32 v145, 31, v144
	v_ashrrev_i32_e32 v147, 31, v146
	v_ashrrev_i32_e32 v149, 31, v148
	v_ashrrev_i32_e32 v151, 31, v150
	v_ashrrev_i32_e32 v153, 31, v152
	v_ashrrev_i32_e32 v155, 31, v154
	v_ashrrev_i32_e32 v157, 31, v156
	v_ashrrev_i32_e32 v159, 31, v158
	v_ashrrev_i32_e32 v161, 31, v160
	v_ashrrev_i32_e32 v163, 31, v162
	v_ashrrev_i32_e32 v165, 31, v164
	v_ashrrev_i32_e32 v167, 31, v166
	v_ashrrev_i32_e32 v169, 31, v168
	s_mov_b32 s7, 0
	v_sub_u32_e32 v176, 0, v175
	s_mov_b32 s13, s45
	s_or_b32 s12, s0, 0x800
	v_lshlrev_b32_e32 v177, 1, v2
	v_lshlrev_b32_e32 v178, 1, v4
	v_mov_b32_e32 v1, v0
	v_mov_b32_e32 v2, v0
	v_mov_b32_e32 v3, v0
	v_mov_b32_e32 v4, v0
	v_mov_b32_e32 v5, v0
	v_mov_b32_e32 v6, v0
	v_mov_b32_e32 v7, v0
	v_mov_b32_e32 v8, v0
	v_mov_b32_e32 v9, v0
	v_mov_b32_e32 v10, v0
	v_mov_b32_e32 v11, v0
	v_mov_b32_e32 v12, v0
	v_mov_b32_e32 v13, v0
	v_mov_b32_e32 v14, v0
	v_mov_b32_e32 v15, v0
	v_mov_b32_e32 v16, v0
	v_mov_b32_e32 v17, v0
	v_mov_b32_e32 v18, v0
	v_mov_b32_e32 v19, v0
	v_mov_b32_e32 v20, v0
	v_mov_b32_e32 v21, v0
	v_mov_b32_e32 v22, v0
	v_mov_b32_e32 v23, v0
	v_mov_b32_e32 v24, v0
	v_mov_b32_e32 v25, v0
	v_mov_b32_e32 v26, v0
	v_mov_b32_e32 v27, v0
	v_mov_b32_e32 v28, v0
	v_mov_b32_e32 v29, v0
	v_mov_b32_e32 v30, v0
	v_mov_b32_e32 v31, v0
	v_readlane_b32 s37, v254, 44
	v_readlane_b32 s38, v254, 45
	v_readlane_b32 s39, v254, 46
	v_readlane_b32 s40, v254, 47
	v_readlane_b32 s41, v254, 48
	v_readlane_b32 s42, v254, 49
	v_readlane_b32 s43, v254, 50
	v_readlane_b32 s44, v254, 51
	v_readlane_b32 s46, v254, 53
	v_readlane_b32 s47, v254, 54
	v_readlane_b32 s48, v254, 55
	v_readlane_b32 s49, v254, 56
	v_readlane_b32 s50, v254, 57
	v_readlane_b32 s51, v254, 58
	s_setprio 2
.LBB0_247:
	s_bitcmp1_b32 s7, 0
	s_cselect_b32 s0, 0xf300, 0
	s_add_i32 s9, s0, 0
	s_lshl_b64 s[0:1], s[12:13], 1
	s_add_u32 s0, s86, s0
	v_lshl_add_u32 v179, v171, 1, s9
	s_addc_u32 s1, s87, s1
	v_add_u32_e32 v70, v179, v177
	s_lshl_b32 s10, s6, 1
	v_add_u32_e32 v50, 0x4000, v70
	s_add_i32 s10, s9, s10
	v_mov_b32_e32 v32, s9
	ds_read2_b64 v[34:37], v50 offset0:128 offset1:132
	ds_read2_b64 v[38:41], v70 offset1:4
	ds_read2_b64 v[42:45], v50 offset0:136 offset1:140
	ds_read2_b64 v[58:61], v70 offset0:8 offset1:12
	ds_read2_b64 v[74:77], v50 offset0:144 offset1:148
	ds_read2_b64 v[78:81], v70 offset0:16 offset1:20
	ds_read2_b64 v[82:85], v50 offset0:152 offset1:156
	ds_read2_b64 v[86:89], v70 offset0:24 offset1:28
	v_lshl_add_u32 v136, v171, 2, s9
	v_add3_u32 v50, s10, v172, v178
	v_add3_u32 v137, s10, v178, v172
	v_add_u32_e32 v71, 0x1000, v70
	v_add_u32_e32 v70, 0x5000, v70
	ds_read_b32 v32, v32 offset:61692
	ds_read_b128 v[90:93], v136 offset:61440
	ds_read_b128 v[54:57], v136 offset:61696
	ds_read_b128 v[94:97], v136 offset:61504
	s_waitcnt vmcnt(0)
	ds_read_b64_tr_b16 v[108:109], v50 offset:53248
	ds_read_b128 v[50:53], v136 offset:61760
	ds_read_b64_tr_b16 v[106:107], v137 offset:55296
	ds_read2_b64 v[98:101], v71 offset0:56 offset1:60
	ds_read2_b64 v[102:105], v70 offset0:184 offset1:188
	ds_read2_b64 v[110:113], v71 offset0:48 offset1:52
	ds_read2_b64 v[116:119], v70 offset0:176 offset1:180
	ds_read2_b64 v[120:123], v71 offset0:40 offset1:44
	ds_read2_b64 v[124:127], v70 offset0:168 offset1:172
	ds_read2_b64 v[128:131], v71 offset0:32 offset1:36
	ds_read2_b64 v[132:135], v70 offset0:160 offset1:164
	v_cvt_pk_f16_f32 v49, v10, v11
	v_cvt_pk_f16_f32 v48, v8, v9
	v_cvt_pk_f16_f32 v47, v14, v15
	v_cvt_pk_f16_f32 v46, v12, v13
	v_cvt_pk_f16_f32 v65, v2, v3
	v_cvt_pk_f16_f32 v64, v0, v1
	v_cvt_pk_f16_f32 v63, v6, v7
	v_cvt_pk_f16_f32 v62, v4, v5
	v_cvt_pk_f16_f32 v69, v22, v23
	v_cvt_pk_f16_f32 v68, v20, v21
	v_cvt_pk_f16_f32 v67, v18, v19
	v_cvt_pk_f16_f32 v66, v16, v17
	v_cvt_pk_f16_f32 v73, v30, v31
	v_cvt_pk_f16_f32 v72, v28, v29
	v_cvt_pk_f16_f32 v71, v26, v27
	v_cvt_pk_f16_f32 v70, v24, v25
	v_add_u32_e32 v180, v136, v176
	s_waitcnt lgkmcnt(0)
; #define MFMA16(a, b, c) __builtin_amdgcn_mfma_f32_16x16x32_f16((a), (b), (c), 0, 0, 0)
; #define CP_F(D, S_) do { _Pragma("unroll") for (int q = 0; q < 8; ++q) D[q] = S_[q]; } while (0)
; __device__ __forceinline__ void phase_scan(h16* Pdn, const h16* Tg, const h16* qkg, const float* gcg, const float* betag, const float* s2g, unsigned char* ldsb) {
;     ...
; #pragma unroll
;                 for (int ti = 0; ti < 4; ++ti) {
;                     if (ti < 3) { LD_A(F1, ti + 1); LD_S(gc1, bt1, vb1, ti + 1); } else LD_T(F1, Tm);
;                     __builtin_amdgcn_sched_barrier(0);
;                     f32x4 ka = {0.f, 0.f, 0.f, 0.f}, qa = {0.f, 0.f, 0.f, 0.f};
; #pragma unroll
;                     for (int kk = 0; kk < 4; ++kk) { ka = MFMA16(F0[2 * kk], Sf[kk], ka); qa = MFMA16(F0[2 * kk + 1], Sf[kk], qa); }
; #pragma unroll
;                     for (int rg = 0; rg < 4; ++rg) { R[ti][rg] = (float)vb0[rg] - bt0[rg] * ka[rg]; O[ti][rg] = gc0[rg] * qa[rg]; }
;                     CP_F(F0, F1); gc0 = gc1; bt0 = bt1; vb0 = vb1;
;                 }
;                 h16x8 Rf[2];
; #pragma unroll
;                 for (int k2 = 0; k2 < 2; ++k2)
; #pragma unroll
;                     for (int rg = 0; rg < 4; ++rg) { Rf[k2][rg] = (h16)R[2 * k2][rg]; Rf[k2][4 + rg] = (h16)R[2 * k2 + 1][rg]; }
;                 LD_T(F1, qkm);
;                 __builtin_amdgcn_sched_barrier(0);
;                 f32x4 Vn[4];
; #pragma unroll
;                 for (int ti = 0; ti < 4; ++ti) {
;                     f32x4 acc = {0.f, 0.f, 0.f, 0.f};
; #pragma unroll
;                     for (int k2 = 0; k2 < 2; ++k2) acc = MFMA16(F0[2 * ti + k2], Rf[k2], acc);
;                     Vn[ti] = acc;
;                 }
;                 CP_F(F0, F1);
;                 h16x8 Vf[2], V2f[2];
; #pragma unroll
;                 for (int k2 = 0; k2 < 2; ++k2) {
;                     const f32x4 gca = *(const f32x4*)(s2s + 32 * k2 + 4 * g), gcb = *(const f32x4*)(s2s + 32 * k2 + 16 + 4 * g);
; #pragma unroll
;                     for (int rg = 0; rg < 4; ++rg) {
;                         Vf[k2][rg] = (h16)Vn[2 * k2][rg]; Vf[k2][4 + rg] = (h16)Vn[2 * k2 + 1][rg];
;                         V2f[k2][rg] = (h16)(Vn[2 * k2][rg] * gca[rg]); V2f[k2][4 + rg] = (h16)(Vn[2 * k2 + 1][rg] * gcb[rg]);
;                     }
;                 }
	v_mfma_f32_16x16x32_f16 v[34:37], v[34:37], v[46:49], 0
	v_add_u32_e32 v181, v180, v177
	v_mfma_f32_16x16x32_f16 v[38:41], v[38:41], v[46:49], 0
	v_mfma_f32_16x16x32_f16 v[34:37], v[42:45], v[62:65], v[34:37]
	v_mfma_f32_16x16x32_f16 v[38:41], v[58:61], v[62:65], v[38:41]
	ds_read_b128 v[42:45], v136 offset:61568
	ds_read_b128 v[58:61], v136 offset:61824
	ds_read_b64_tr_b16 v[114:115], v137 offset:57344
	v_mfma_f32_16x16x32_f16 v[34:37], v[74:77], v[66:69], v[34:37]
	v_mfma_f32_16x16x32_f16 v[38:41], v[78:81], v[66:69], v[38:41]
	v_mfma_f32_16x16x32_f16 v[74:77], v[82:85], v[70:73], v[34:37]
	v_mfma_f32_16x16x32_f16 v[34:37], v[86:89], v[70:73], v[38:41]
	s_nop 5
	v_add_u32_e32 v38, 0x2000, v181
	v_add_u32_e32 v39, 0x6000, v181
	v_pk_mul_f32 v[36:37], v[92:93], v[36:37]
	v_pk_mul_f32 v[34:35], v[90:91], v[34:35]
	ds_read2_b64 v[90:93], v38 offset0:88 offset1:92
	ds_read2_b64 v[86:89], v39 offset0:216 offset1:220
	ds_read2_b64 v[204:207], v38 offset0:80 offset1:84
	ds_read2_b64 v[208:211], v39 offset0:208 offset1:212
	ds_read2_b64 v[212:215], v38 offset0:72 offset1:76
	ds_read2_b64 v[216:219], v39 offset0:200 offset1:204
	ds_read2_b64 v[220:223], v38 offset0:64 offset1:68
	ds_read2_b64 v[224:227], v39 offset0:192 offset1:196
	v_mfma_f32_16x16x32_f16 v[38:41], v[132:135], v[46:49], 0
	v_mfma_f32_16x16x32_f16 v[78:81], v[128:131], v[46:49], 0
	v_mfma_f32_16x16x32_f16 v[38:41], v[124:127], v[62:65], v[38:41]
	v_mfma_f32_16x16x32_f16 v[78:81], v[120:123], v[62:65], v[78:81]
	v_mfma_f32_16x16x32_f16 v[38:41], v[116:119], v[66:69], v[38:41]
	v_mfma_f32_16x16x32_f16 v[78:81], v[110:113], v[66:69], v[78:81]
	v_mfma_f32_16x16x32_f16 v[82:85], v[102:105], v[70:73], v[38:41]
	v_mfma_f32_16x16x32_f16 v[38:41], v[98:101], v[70:73], v[78:81]
	ds_read_b128 v[118:121], v136 offset:61632
	s_nop 4
	ds_read_b128 v[78:81], v136 offset:61888
	ds_read_b64_tr_b16 v[116:117], v137 offset:59392
	v_pk_mul_f32 v[38:39], v[94:95], v[38:39]
	v_add_u32_e32 v94, 0x3000, v181
	v_add_u32_e32 v95, 0x7000, v181
	ds_read2_b64 v[122:125], v94 offset0:120 offset1:124
	ds_read2_b64 v[228:231], v95 offset0:248 offset1:252
	ds_read2_b64 v[232:235], v94 offset0:112 offset1:116
	ds_read2_b64 v[236:239], v95 offset0:240 offset1:244
	ds_read2_b64 v[240:243], v94 offset0:104 offset1:108
	ds_read2_b64 v[244:247], v95 offset0:232 offset1:236
	ds_read2_b64 v[248:251], v94 offset0:96 offset1:100
	ds_read2_b64 v[196:199], v95 offset0:224 offset1:228
	v_pk_mul_f32 v[40:41], v[96:97], v[40:41]
	s_waitcnt lgkmcnt(12)
	v_mfma_f32_16x16x32_f16 v[98:101], v[220:223], v[46:49], 0
	v_add_u32_e32 v130, v180, v173
	v_add_u32_e32 v102, 0x9800, v130
	v_add_u32_e32 v126, 0x9000, v130
	s_waitcnt lgkmcnt(11)
	v_mfma_f32_16x16x32_f16 v[94:97], v[224:227], v[46:49], 0
	v_add_u32_e32 v134, 0x8800, v130
	v_mfma_f32_16x16x32_f16 v[98:101], v[212:215], v[62:65], v[98:101]
	v_mfma_f32_16x16x32_f16 v[94:97], v[216:219], v[62:65], v[94:97]
	v_mfma_f32_16x16x32_f16 v[98:101], v[204:207], v[66:69], v[98:101]
	v_mfma_f32_16x16x32_f16 v[94:97], v[208:211], v[66:69], v[94:97]
	v_mfma_f32_16x16x32_f16 v[90:93], v[90:93], v[70:73], v[98:101]
	v_mfma_f32_16x16x32_f16 v[86:89], v[86:89], v[70:73], v[94:97]
	s_nop 5
	v_add_u32_e32 v94, 0xa000, v130
	v_pk_mul_f32 v[44:45], v[44:45], v[92:93]
	v_pk_mul_f32 v[42:43], v[42:43], v[90:91]
	ds_read2_b64 v[90:93], v94 offset0:104 offset1:108
	ds_read2_b64 v[94:97], v94 offset0:96 offset1:100
	ds_read2_b64 v[98:101], v102 offset0:72 offset1:76
	ds_read2_b64 v[102:105], v102 offset0:64 offset1:68
	ds_read2_b64 v[110:113], v126 offset0:40 offset1:44
	ds_read2_b64 v[126:129], v126 offset0:32 offset1:36
	ds_read2_b64 v[130:133], v134 offset0:8 offset1:12
	ds_read2_b64 v[134:137], v134 offset1:4
	s_waitcnt lgkmcnt(8)
	v_mfma_f32_16x16x32_f16 v[196:199], v[196:199], v[46:49], 0
	v_mfma_f32_16x16x32_f16 v[46:49], v[248:251], v[46:49], 0
	v_mfma_f32_16x16x32_f16 v[196:199], v[244:247], v[62:65], v[196:199]
	v_mfma_f32_16x16x32_f16 v[46:49], v[240:243], v[62:65], v[46:49]
	v_mfma_f32_16x16x32_f16 v[62:65], v[236:239], v[66:69], v[196:199]
	v_mfma_f32_16x16x32_f16 v[46:49], v[232:235], v[66:69], v[46:49]
	v_cvt_f32_f16_e32 v66, v108
	v_cvt_f32_f16_sdwa v67, v108 dst_sel:DWORD dst_unused:UNUSED_PAD src0_sel:WORD_1
	v_pk_fma_f32 v[54:55], v[54:55], v[74:75], v[66:67] neg_lo:[1,0,0] neg_hi:[1,0,0]
	s_nop 0
	v_cvt_pk_f16_f32 v66, v54, v55
	v_cvt_f32_f16_e32 v54, v106
	v_cvt_f32_f16_sdwa v55, v106 dst_sel:DWORD dst_unused:UNUSED_PAD src0_sel:WORD_1
	v_mfma_f32_16x16x32_f16 v[62:65], v[228:231], v[70:73], v[62:65]
	v_fma_f32 v50, -v50, v82, v54
	v_fma_f32 v51, -v51, v83, v55
	v_cvt_pk_f16_f32 v68, v50, v51
	v_cvt_f32_f16_e32 v50, v109
	v_cvt_f32_f16_sdwa v51, v109 dst_sel:DWORD dst_unused:UNUSED_PAD src0_sel:WORD_1
	v_cvt_f32_f16_e32 v54, v115
	v_cvt_f32_f16_sdwa v55, v115 dst_sel:DWORD dst_unused:UNUSED_PAD src0_sel:WORD_1
	v_mfma_f32_16x16x32_f16 v[46:49], v[122:125], v[70:73], v[46:49]
	v_fma_f32 v50, -v56, v76, v50
	v_fma_f32 v51, -v57, v77, v51
	v_pk_fma_f32 v[54:55], v[60:61], v[88:89], v[54:55] neg_lo:[1,0,0] neg_hi:[1,0,0]
	v_cvt_pk_f16_f32 v67, v50, v51
	v_cvt_f32_f16_e32 v50, v107
	v_cvt_f32_f16_sdwa v51, v107 dst_sel:DWORD dst_unused:UNUSED_PAD src0_sel:WORD_1
	s_nop 1
	v_pk_mul_f32 v[48:49], v[120:121], v[48:49]
	v_pk_mul_f32 v[46:47], v[118:119], v[46:47]
	v_pk_fma_f32 v[50:51], v[52:53], v[84:85], v[50:51] neg_lo:[1,0,0] neg_hi:[1,0,0]
	s_nop 0
	v_cvt_pk_f16_f32 v69, v50, v51
	v_cvt_f32_f16_e32 v50, v114
	v_cvt_f32_f16_sdwa v51, v114 dst_sel:DWORD dst_unused:UNUSED_PAD src0_sel:WORD_1
	v_cvt_f32_f16_e32 v52, v116
	v_cvt_f32_f16_sdwa v53, v116 dst_sel:DWORD dst_unused:UNUSED_PAD src0_sel:WORD_1
	v_pk_fma_f32 v[50:51], v[58:59], v[86:87], v[50:51] neg_lo:[1,0,0] neg_hi:[1,0,0]
	s_nop 0
	v_cvt_pk_f16_f32 v50, v50, v51
	v_cvt_pk_f16_f32 v51, v54, v55
	v_cvt_f32_f16_e32 v54, v117
	v_cvt_f32_f16_sdwa v55, v117 dst_sel:DWORD dst_unused:UNUSED_PAD src0_sel:WORD_1
	v_pk_fma_f32 v[52:53], v[78:79], v[62:63], v[52:53] neg_lo:[1,0,0] neg_hi:[1,0,0]
	v_pk_fma_f32 v[54:55], v[80:81], v[64:65], v[54:55] neg_lo:[1,0,0] neg_hi:[1,0,0]
	v_cvt_pk_f16_f32 v52, v52, v53
	v_cvt_pk_f16_f32 v53, v54, v55
	v_add_u32_e32 v54, v179, v173
	v_add_u32_e32 v55, 0xa800, v54
	ds_read2_b64 v[118:121], v55 offset0:128 offset1:132
	ds_read2_b64 v[122:125], v55 offset0:136 offset1:140
	v_add_u32_e32 v55, 0xb000, v54
	ds_read2_b64 v[114:117], v55 offset0:160 offset1:164
	ds_read2_b64 v[106:109], v55 offset0:168 offset1:172
	v_add_u32_e32 v55, 0xb800, v54
	v_add_u32_e32 v54, 0xc000, v54
	ds_read2_b64 v[86:89], v55 offset0:192 offset1:196
	ds_read2_b64 v[82:85], v55 offset0:200 offset1:204
	ds_read2_b64 v[62:65], v54 offset0:224 offset1:228
	ds_read2_b64 v[58:61], v54 offset0:232 offset1:236
	s_waitcnt lgkmcnt(8)
; #define MFMA16(a, b, c) __builtin_amdgcn_mfma_f32_16x16x32_f16((a), (b), (c), 0, 0, 0)
; #define CP_F(D, S_) do { _Pragma("unroll") for (int q = 0; q < 8; ++q) D[q] = S_[q]; } while (0)
; __device__ __forceinline__ void phase_scan(h16* Pdn, const h16* Tg, const h16* qkg, const float* gcg, const float* betag, const float* s2g, unsigned char* ldsb) {
;     ...
;                 f32x4 Vn[4];
; #pragma unroll
;                 for (int ti = 0; ti < 4; ++ti) {
;                     f32x4 acc = {0.f, 0.f, 0.f, 0.f};
; #pragma unroll
;                     for (int k2 = 0; k2 < 2; ++k2) acc = MFMA16(F0[2 * ti + k2], Rf[k2], acc);
;                     Vn[ti] = acc;
;                 }
;                 CP_F(F0, F1);
;                 h16x8 Vf[2], V2f[2];
; #pragma unroll
;                 for (int k2 = 0; k2 < 2; ++k2) {
;                     const f32x4 gca = *(const f32x4*)(s2s + 32 * k2 + 4 * g), gcb = *(const f32x4*)(s2s + 32 * k2 + 16 + 4 * g);
; #pragma unroll
;                     for (int rg = 0; rg < 4; ++rg) {
;                         Vf[k2][rg] = (h16)Vn[2 * k2][rg]; Vf[k2][4 + rg] = (h16)Vn[2 * k2 + 1][rg];
;                         V2f[k2][rg] = (h16)(Vn[2 * k2][rg] * gca[rg]); V2f[k2][4 + rg] = (h16)(Vn[2 * k2 + 1][rg] * gcb[rg]);
;                     }
;                 }
;                 LD_K(F1, 0);
;                 __builtin_amdgcn_sched_barrier(0);
; #pragma unroll
;                 for (int ti = 0; ti < 4; ++ti) {
; #pragma unroll
;                     for (int k2 = 0; k2 < 2; ++k2) O[ti] = MFMA16(F0[2 * ti + k2], Vf[k2], O[ti]);
; #pragma unroll
;                     for (int rg = 0; rg < 4; ++rg) {
;                         const int i = 16 * ti + 4 * g + rg;
;                         ob[i * 4096 + 16 * w + fr] = (h16)O[ti][rg];
;                     }
;                 }
;                 CP_F(F0, F1);
;                 LD_K(F1, 4);
;                 __builtin_amdgcn_sched_barrier(0);
; #pragma unroll
;                 for (int t = 0; t < 4; ++t) {
;                     f32x4 acc = S[t] * e_last;
; #pragma unroll
;                     for (int k2 = 0; k2 < 2; ++k2) acc = MFMA16(F0[2 * t + k2], V2f[k2], acc);
;                     S[t] = acc;
;                 }
;                 __builtin_amdgcn_sched_barrier(0);
; #pragma unroll
;                 for (int t = 0; t < 4; ++t) {
;                     f32x4 acc = S[4 + t] * e_last;
	v_mfma_f32_16x16x32_f16 v[54:57], v[134:137], v[66:69], 0
	v_mfma_f32_16x16x32_f16 v[70:73], v[126:129], v[66:69], 0
	v_mfma_f32_16x16x32_f16 v[74:77], v[102:105], v[66:69], 0
	v_add3_u32 v104, s9, v178, v174
	v_mfma_f32_16x16x32_f16 v[66:69], v[94:97], v[66:69], 0
	v_mfma_f32_16x16x32_f16 v[66:69], v[90:93], v[50:53], v[66:69]
	v_add_u32_e32 v92, v179, v175
	v_mfma_f32_16x16x32_f16 v[54:57], v[130:133], v[50:53], v[54:57]
	v_mfma_f32_16x16x32_f16 v[70:73], v[110:113], v[50:53], v[70:73]
	s_nop 4
	v_cvt_pk_f16_f32 v128, v66, v67
	s_nop 0
	v_cvt_pk_f16_f32 v110, v54, v55
	v_cvt_pk_f16_f32 v111, v56, v57
	v_mfma_f32_16x16x32_f16 v[74:77], v[98:101], v[50:53], v[74:77]
	ds_read_b128 v[50:53], v92 offset:61952
	ds_read_b128 v[78:81], v92 offset:62016
	v_cvt_pk_f16_f32 v113, v72, v73
	v_cvt_pk_f16_f32 v112, v70, v71
	v_cvt_pk_f16_f32 v129, v68, v69
	s_waitcnt lgkmcnt(1)
	v_pk_mul_f32 v[90:91], v[56:57], v[52:53]
	v_mul_f32_e32 v51, v55, v51
	v_fma_mixlo_f16 v93, v54, v50, 0
	v_pk_mov_b32 v[50:51], v[50:51], v[90:91] op_sel:[1,0]
	s_waitcnt lgkmcnt(0)
	v_pk_mul_f32 v[90:91], v[70:71], v[78:79]
	v_mul_f32_e32 v80, v72, v80
	v_pk_mov_b32 v[90:91], v[90:91], v[80:81] op_sel:[1,0]
	v_pk_mov_b32 v[54:55], v[56:57], v[70:71] op_sel:[1,0]
	v_pk_mov_b32 v[52:53], v[52:53], v[78:79] op_sel:[1,0]
	v_cvt_pk_f16_f32 v80, v90, v91
	v_pk_mul_f32 v[52:53], v[54:55], v[52:53]
	v_cvt_pk_f16_f32 v51, v50, v51
	v_cvt_pk_f16_f32 v52, v52, v53
	v_lshrrev_b32_e32 v53, 16, v80
	v_fma_mixhi_f16 v53, v73, v81, 0
	ds_read_b128 v[54:57], v92 offset:62080
	ds_read_b128 v[70:73], v92 offset:62144
	v_pack_b32_f16 v50, v93, v51
	v_alignbit_b32 v51, v52, v51, 16
	v_alignbit_b32 v52, v80, v52, 16
	s_waitcnt lgkmcnt(1)
	v_pk_mul_f32 v[78:79], v[76:77], v[56:57]
	v_mul_f32_e32 v55, v75, v55
	v_fma_mixlo_f16 v80, v74, v54, 0
	v_pk_mov_b32 v[54:55], v[54:55], v[78:79] op_sel:[1,0]
	s_waitcnt lgkmcnt(0)
	v_pk_mul_f32 v[78:79], v[66:67], v[70:71]
	v_mul_f32_e32 v72, v68, v72
	v_pk_mov_b32 v[78:79], v[78:79], v[72:73] op_sel:[1,0]
	v_pk_mov_b32 v[66:67], v[76:77], v[66:67] op_sel:[1,0]
	v_pk_mov_b32 v[56:57], v[56:57], v[70:71] op_sel:[1,0]
	v_cvt_pk_f16_f32 v72, v78, v79
	v_pk_mul_f32 v[56:57], v[66:67], v[56:57]
	v_cvt_pk_f16_f32 v55, v54, v55
	v_cvt_pk_f16_f32 v56, v56, v57
	v_lshrrev_b32_e32 v57, 16, v72
	v_pack_b32_f16 v54, v80, v55
	v_cvt_pk_f16_f32 v127, v76, v77
	v_cvt_pk_f16_f32 v126, v74, v75
	v_alignbit_b32 v55, v56, v55, 16
	v_alignbit_b32 v56, v72, v56, 16
	v_fma_mixhi_f16 v57, v69, v73, 0
	ds_read_b64_tr_b16 v[76:77], v104 offset:21760
	ds_read_b64_tr_b16 v[74:75], v104 offset:17408
	ds_read_b64_tr_b16 v[66:67], v104 offset:17440
	ds_read_b64_tr_b16 v[78:79], v104 offset:26112
	ds_read_b64_tr_b16 v[80:81], v104 offset:30464
	ds_read_b64_tr_b16 v[68:69], v104 offset:21792
	ds_read_b64_tr_b16 v[70:71], v104 offset:26144
	ds_read_b64_tr_b16 v[72:73], v104 offset:30496
	ds_read_b64_tr_b16 v[90:91], v104 offset:17472
	ds_read_b64_tr_b16 v[92:93], v104 offset:21824
	ds_read_b64_tr_b16 v[94:95], v104 offset:26176
	ds_read_b64_tr_b16 v[96:97], v104 offset:30528
	ds_read_b64_tr_b16 v[98:99], v104 offset:17504
	ds_read_b64_tr_b16 v[100:101], v104 offset:21856
	ds_read_b64_tr_b16 v[102:103], v104 offset:26208
	ds_read_b64_tr_b16 v[104:105], v104 offset:30560
	v_mfma_f32_16x16x32_f16 v[34:37], v[118:121], v[110:113], v[34:37]
	v_lshl_add_u64 v[118:119], v[138:139], 1, s[0:1]
	v_mfma_f32_16x16x32_f16 v[34:37], v[122:125], v[126:129], v[34:37]
	s_nop 7
	v_cvt_f16_f32_e32 v34, v34
	v_cvt_f16_f32_e32 v36, v36
	global_store_short v[118:119], v34, off
	v_cvt_f16_f32_e32 v118, v35
	v_lshl_add_u64 v[34:35], v[140:141], 1, s[0:1]
	global_store_short v[34:35], v118, off
	v_lshl_add_u64 v[34:35], v[142:143], 1, s[0:1]
	global_store_short v[34:35], v36, off
	v_cvt_f16_f32_e32 v36, v37
	v_lshl_add_u64 v[34:35], v[144:145], 1, s[0:1]
	global_store_short v[34:35], v36, off
	v_mfma_f32_16x16x32_f16 v[34:37], v[114:117], v[110:113], v[38:41]
	v_mfma_f32_16x16x32_f16 v[34:37], v[106:109], v[126:129], v[34:37]
	s_nop 1
	v_lshl_add_u64 v[38:39], v[146:147], 1, s[0:1]
	s_nop 4
	v_cvt_f16_f32_e32 v34, v34
	v_cvt_f16_f32_e32 v36, v36
	global_store_short v[38:39], v34, off
	v_cvt_f16_f32_e32 v38, v35
	v_lshl_add_u64 v[34:35], v[148:149], 1, s[0:1]
	global_store_short v[34:35], v38, off
	v_lshl_add_u64 v[34:35], v[150:151], 1, s[0:1]
	global_store_short v[34:35], v36, off
	v_cvt_f16_f32_e32 v36, v37
	v_lshl_add_u64 v[34:35], v[152:153], 1, s[0:1]
	v_lshl_add_u64 v[38:39], v[154:155], 1, s[0:1]
	global_store_short v[34:35], v36, off
	v_mfma_f32_16x16x32_f16 v[34:37], v[86:89], v[110:113], v[42:45]
	v_add3_u32 v88, s9, v174, v178
	v_mfma_f32_16x16x32_f16 v[34:37], v[82:85], v[126:129], v[34:37]
	s_nop 7
	v_cvt_f16_f32_e32 v34, v34
	v_cvt_f16_f32_e32 v36, v36
	global_store_short v[38:39], v34, off
	v_cvt_f16_f32_e32 v38, v35
	v_lshl_add_u64 v[34:35], v[156:157], 1, s[0:1]
	global_store_short v[34:35], v38, off
	v_lshl_add_u64 v[34:35], v[158:159], 1, s[0:1]
	global_store_short v[34:35], v36, off
	v_cvt_f16_f32_e32 v36, v37
	v_lshl_add_u64 v[34:35], v[160:161], 1, s[0:1]
	v_lshl_add_u64 v[38:39], v[162:163], 1, s[0:1]
	global_store_short v[34:35], v36, off
	v_mfma_f32_16x16x32_f16 v[34:37], v[62:65], v[110:113], v[46:49]
	v_mfma_f32_16x16x32_f16 v[34:37], v[58:61], v[126:129], v[34:37]
	s_nop 7
	v_cvt_f16_f32_e32 v34, v34
	v_cvt_f16_f32_e32 v36, v36
	global_store_short v[38:39], v34, off
	v_cvt_f16_f32_e32 v38, v35
	v_lshl_add_u64 v[34:35], v[164:165], 1, s[0:1]
	global_store_short v[34:35], v38, off
	v_lshl_add_u64 v[34:35], v[166:167], 1, s[0:1]
	global_store_short v[34:35], v36, off
	v_cvt_f16_f32_e32 v36, v37
	v_lshl_add_u64 v[34:35], v[168:169], 1, s[0:1]
	global_store_short v[34:35], v36, off
	ds_read_b64_tr_b16 v[36:37], v88 offset:21888
	ds_read_b64_tr_b16 v[34:35], v88 offset:17536
	ds_read_b64_tr_b16 v[38:39], v88 offset:17568
	ds_read_b64_tr_b16 v[42:43], v88 offset:26240
	ds_read_b64_tr_b16 v[44:45], v88 offset:30592
	ds_read_b64_tr_b16 v[40:41], v88 offset:21920
	ds_read_b64_tr_b16 v[46:47], v88 offset:26272
	ds_read_b64_tr_b16 v[48:49], v88 offset:30624
	ds_read_b64_tr_b16 v[58:59], v88 offset:17600
	ds_read_b64_tr_b16 v[60:61], v88 offset:21952
	ds_read_b64_tr_b16 v[62:63], v88 offset:26304
	ds_read_b64_tr_b16 v[64:65], v88 offset:30656
	ds_read_b64_tr_b16 v[82:83], v88 offset:17632
	ds_read_b64_tr_b16 v[84:85], v88 offset:21984
	ds_read_b64_tr_b16 v[86:87], v88 offset:26336
	ds_read_b64_tr_b16 v[88:89], v88 offset:30688
	v_pk_mul_f32 v[14:15], v[14:15], v[32:33] op_sel_hi:[1,0]
	v_pk_mul_f32 v[12:13], v[12:13], v[32:33] op_sel_hi:[1,0]
	v_pk_mul_f32 v[10:11], v[10:11], v[32:33] op_sel_hi:[1,0]
	v_pk_mul_f32 v[8:9], v[8:9], v[32:33] op_sel_hi:[1,0]
	v_pk_mul_f32 v[6:7], v[6:7], v[32:33] op_sel_hi:[1,0]
	v_pk_mul_f32 v[4:5], v[4:5], v[32:33] op_sel_hi:[1,0]
	v_pk_mul_f32 v[2:3], v[2:3], v[32:33] op_sel_hi:[1,0]
	v_pk_mul_f32 v[0:1], v[0:1], v[32:33] op_sel_hi:[1,0]
	s_waitcnt lgkmcnt(14)
; #define LDS_BARRIER() do { asm volatile("s_waitcnt lgkmcnt(0)" ::: "memory"); __builtin_amdgcn_s_barrier(); asm volatile("" ::: "memory"); } while (0)
; #define MFMA16(a, b, c) __builtin_amdgcn_mfma_f32_16x16x32_f16((a), (b), (c), 0, 0, 0)
; __device__ __forceinline__ void phase_scan(h16* Pdn, const h16* Tg, const h16* qkg, const float* gcg, const float* betag, const float* s2g, unsigned char* ldsb) {
;     ...
; #pragma unroll
;                 for (int t = 0; t < 4; ++t) {
;                     f32x4 acc = S[t] * e_last;
; #pragma unroll
;                     for (int k2 = 0; k2 < 2; ++k2) acc = MFMA16(F0[2 * t + k2], V2f[k2], acc);
;                     S[t] = acc;
;                 }
;                 __builtin_amdgcn_sched_barrier(0);
; #pragma unroll
;                 for (int t = 0; t < 4; ++t) {
;                     f32x4 acc = S[4 + t] * e_last;
; #pragma unroll
;                     for (int k2 = 0; k2 < 2; ++k2) acc = MFMA16(F1[2 * t + k2], V2f[k2], acc);
;                     S[4 + t] = acc;
;                 }
;     ...
;             }
;             LDS_BARRIER();
;         }
	v_mfma_f32_16x16x32_f16 v[12:15], v[74:77], v[50:53], v[12:15]
	v_mfma_f32_16x16x32_f16 v[8:11], v[66:69], v[50:53], v[8:11]
	v_mfma_f32_16x16x32_f16 v[4:7], v[90:93], v[50:53], v[4:7]
	v_mfma_f32_16x16x32_f16 v[0:3], v[98:101], v[50:53], v[0:3]
	v_mfma_f32_16x16x32_f16 v[12:15], v[78:81], v[54:57], v[12:15]
	v_mfma_f32_16x16x32_f16 v[8:11], v[70:73], v[54:57], v[8:11]
	v_mfma_f32_16x16x32_f16 v[4:7], v[94:97], v[54:57], v[4:7]
	v_mfma_f32_16x16x32_f16 v[0:3], v[102:105], v[54:57], v[0:3]
	v_mul_f32_e64 v18, v18, v32
	v_mul_f32_e64 v19, v19, v32
	v_pk_mul_f32 v[16:17], v[16:17], v[32:33] op_sel_hi:[1,0]
	v_pk_mul_f32 v[22:23], v[22:23], v[32:33] op_sel_hi:[1,0]
	v_pk_mul_f32 v[20:21], v[20:21], v[32:33] op_sel_hi:[1,0]
	v_pk_mul_f32 v[26:27], v[26:27], v[32:33] op_sel_hi:[1,0]
	v_pk_mul_f32 v[24:25], v[24:25], v[32:33] op_sel_hi:[1,0]
	v_pk_mul_f32 v[30:31], v[30:31], v[32:33] op_sel_hi:[1,0]
	v_pk_mul_f32 v[28:29], v[28:29], v[32:33] op_sel_hi:[1,0]
	v_mfma_f32_16x16x32_f16 v[16:19], v[34:37], v[50:53], v[16:19]
	s_waitcnt lgkmcnt(0)
	s_barrier
	s_waitcnt lgkmcnt(10)
	v_mfma_f32_16x16x32_f16 v[20:23], v[38:41], v[50:53], v[20:23]
	s_add_i32 s7, s7, 1
	s_add_i32 s12, s12, 0x40000
	s_cmp_eq_u32 s7, 64
	s_waitcnt lgkmcnt(6)
	v_mfma_f32_16x16x32_f16 v[24:27], v[58:61], v[50:53], v[24:27]
	s_waitcnt lgkmcnt(2)
	v_mfma_f32_16x16x32_f16 v[28:31], v[82:85], v[50:53], v[28:31]
	v_mfma_f32_16x16x32_f16 v[16:19], v[42:45], v[54:57], v[16:19]
	v_mfma_f32_16x16x32_f16 v[20:23], v[46:49], v[54:57], v[20:23]
	v_mfma_f32_16x16x32_f16 v[24:27], v[62:65], v[54:57], v[24:27]
	s_waitcnt lgkmcnt(0)
	v_mfma_f32_16x16x32_f16 v[28:31], v[86:89], v[54:57], v[28:31]
	s_cbranch_scc0 .LBB0_247
	s_setprio 0
	v_writelane_b32 v254, s4, 43
	s_mov_b64 s[0:1], 0
	s_nop 0
	v_writelane_b32 v254, s5, 44
	v_writelane_b32 v254, s6, 45
	v_writelane_b32 v254, s7, 46
	v_writelane_b32 v254, s8, 47
	v_writelane_b32 v254, s9, 48
	v_writelane_b32 v254, s10, 49
	v_writelane_b32 v254, s11, 50
	v_writelane_b32 v254, s12, 51
	v_writelane_b32 v254, s13, 52
	v_writelane_b32 v254, s14, 53
	v_writelane_b32 v254, s15, 54
	v_writelane_b32 v254, s16, 55
	v_writelane_b32 v254, s17, 56
	v_writelane_b32 v254, s18, 57
	v_writelane_b32 v254, s19, 58
